# v80 + SSD Ydiag blocks (u=1..3): four G-fragment LDS reads issued up front with counted waits
# baseline (speedup 1.0000x reference)
; #define LAS __attribute__((address_space(3)))
; __device__ __forceinline__ void ssd_phase(const bf16_t* XBC, const float* DT  , const ss_t* SSq, const float* dtb, const bf16_t* Z, const float* a_log, const float* d_skip, bf16_t* YS, LAS unsigned char* lds, int tid, int wid, int lane, int bid, int G) {
;     ...
; #pragma unroll
;             for (int u = 0; u < 4; ++u) {
;                 if (2 * u <= wid) {
;                     u32x4 gq; gq.x = gp[2 * u][0]; gq.y = gp[2 * u][1]; gq.z = gp[2 * u + 1][0]; gq.w = gp[2 * u + 1][1];
;                     const bf16x8 gfr = __builtin_bit_cast(bf16x8, gq);
; #pragma unroll
;                     for (int pt = 0; pt < 4; ++pt) { const u32x2 lo = *(const LAS u32x2*)(XT + (16 * pt + fr) * SS_RS + 32 * u + 4 * fq), hi = *(const LAS u32x2*)(XT + (16 * pt + fr) * SS_RS + 32 * u + 16 + 4 * fq);
;                         u32x4 xq; xq.x = lo.x; xq.y = lo.y; xq.z = hi.x; xq.w = hi.y;
;                         accd[pt] = __builtin_amdgcn_mfma_f32_16x16x32_bf16(__builtin_bit_cast(bf16x8, xq), gfr, accd[pt], 0, 0, 0); }
;                 }
;                 __builtin_amdgcn_sched_barrier(0);
;             }
.LBB0_140:
	s_and_b64 vcc, exec, s[86:87]
	s_cbranch_vccnz .LBB0_142
	ds_read2_b64 v[240:243], v219 offset1:4
	ds_read2_b64 v[244:247], v220 offset1:4
	ds_read2_b64 v[248:251], v221 offset1:4
	ds_read2_b64 v[148:151], v222 offset1:4
	s_waitcnt lgkmcnt(3)
	v_mfma_f32_16x16x32_bf16 v[102:105], v[240:243], v[12:15], v[102:105]
	s_waitcnt lgkmcnt(2)
	v_mfma_f32_16x16x32_bf16 v[90:93], v[244:247], v[12:15], v[90:93]
	s_waitcnt lgkmcnt(1)
	v_mfma_f32_16x16x32_bf16 v[8:11], v[248:251], v[12:15], v[8:11]
	s_waitcnt lgkmcnt(0)
	v_mfma_f32_16x16x32_bf16 v[4:7], v[148:151], v[12:15], v[4:7]
.LBB0_142:
	s_mov_b32 s86, 0x800000
	s_and_b64 vcc, exec, s[88:89]
	s_cbranch_vccnz .LBB0_144
	ds_read2_b64 v[240:243], v223 offset1:4
	ds_read2_b64 v[244:247], v224 offset1:4
	ds_read2_b64 v[248:251], v225 offset1:4
	ds_read2_b64 v[148:151], v226 offset1:4
	s_waitcnt lgkmcnt(3)
	v_mfma_f32_16x16x32_bf16 v[102:105], v[240:243], v[94:97], v[102:105]
	s_waitcnt lgkmcnt(2)
	v_mfma_f32_16x16x32_bf16 v[90:93], v[244:247], v[94:97], v[90:93]
	s_waitcnt lgkmcnt(1)
	v_mfma_f32_16x16x32_bf16 v[8:11], v[248:251], v[94:97], v[8:11]
	s_waitcnt lgkmcnt(0)
	v_mfma_f32_16x16x32_bf16 v[4:7], v[148:151], v[94:97], v[4:7]
.LBB0_144:
	s_and_b64 vcc, exec, s[90:91]
	s_cbranch_vccnz .LBB0_100
	ds_read2_b64 v[240:243], v227 offset1:4
	ds_read2_b64 v[244:247], v228 offset1:4
	ds_read2_b64 v[248:251], v229 offset1:4
	ds_read2_b64 v[148:151], v230 offset1:4
	s_waitcnt lgkmcnt(3)
	v_mfma_f32_16x16x32_bf16 v[102:105], v[240:243], v[98:101], v[102:105]
	s_waitcnt lgkmcnt(2)
	v_mfma_f32_16x16x32_bf16 v[90:93], v[244:247], v[98:101], v[90:93]
	s_waitcnt lgkmcnt(1)
	v_mfma_f32_16x16x32_bf16 v[8:11], v[248:251], v[98:101], v[8:11]
	s_waitcnt lgkmcnt(0)
	v_mfma_f32_16x16x32_bf16 v[4:7], v[148:151], v[98:101], v[4:7]
	s_branch .LBB0_100
